# phase-1 stage order: workgroups on odd XCDs run their SGU units first, then attention and conv (bandwidth-bound SGU of half the chip overlaps compute-bound attention of the other half)
# speedup vs baseline: 1.0017x; 1.0017x over previous
; #define LAS __attribute__((address_space(3)))
; __global__ void __launch_bounds__(NTHREADS, 2) fwd_megakernel(Args a_unused) {
;     extern __shared__ __attribute__((aligned(16))) unsigned char lds_raw[];
;     LAS unsigned char* lds = (LAS unsigned char*)lds_raw;
;     CArgs ap0 = (CArgs)__builtin_amdgcn_kernarg_segment_ptr();
;     const int lo = ap0->lo, hi = ap0->hi;
;     const int wave = __builtin_amdgcn_readfirstlane((int)threadIdx.x >> 6);
;     const bool t0 = (threadIdx.x == 0);
;     volatile LAS unsigned* bst = (volatile LAS unsigned*)(lds + 131072 + 1024);
;     if (t0) { bst[0] = 0u; bst[1] = 0u; }
;     __syncthreads();
;     const XcdBarrier gbar = xcd_barrier_post((unsigned*)ap0->ws, bst, t0);
_Z14fwd_megakernel4Args:
	s_mov_b32 s101, 0
	s_load_dwordx2 s[72:73], s[0:1], 0xe0
	v_and_b32_e32 v1, 0x3ff, v0
	s_mov_b64 s[96:97], s[0:1]
	v_readfirstlane_b32 s7, v1
	v_cmp_eq_u32_e64 s[4:5], 0, v1
	s_mov_b64 s[0:1], exec
	s_nop 0
	v_writelane_b32 v253, s4, 0
	s_nop 1
	v_writelane_b32 v253, s5, 1
	s_and_b64 s[4:5], s[0:1], s[4:5]
	s_mov_b64 exec, s[4:5]
	s_cbranch_execz .LBB0_2
	s_add_i32 s3, 0, 0x20400
	v_mov_b32_e32 v2, 0
	v_mov_b32_e32 v3, s3
	s_add_i32 s3, 0, 0x20404
	ds_write_b32 v3, v2
	v_mov_b32_e32 v3, s3
	ds_write_b32 v3, v2

; __device__ __forceinline__ int lane_op() { unsigned z = 0u; asm volatile("" : "+v"(z)); return (int)__builtin_amdgcn_mbcnt_hi(~0u, __builtin_amdgcn_mbcnt_lo(~0u, z)); }
; #define PH_ON(bit) if constexpr ((PHMASK & (bit)) != 0)
; __global__ void __launch_bounds__(NTHREADS, 2) fwd_megakernel(Args a_unused) {
;     ...
;                 const int per = (1024 + G - 1) / G;
;                 PH_ON(512) {
;                     const int lane = lane_op();
;                     const float la = wave_sum(ap->in[I_LQ1][l * 64 + lane] * ap->in[I_LK1][l * 64 + lane]), lb = wave_sum(ap->in[I_LQ2][l * 64 + lane] * ap->in[I_LK2][l * 64 + lane]);
;                     const float lam_init = 0.8f - 0.6f * expf(-0.3f * (float)l);
;                     const float lam = __int_as_float(__builtin_amdgcn_readfirstlane(__float_as_int(expf(la) - expf(lb) + lam_init)));
;                     const float oscale = __int_as_float(__builtin_amdgcn_readfirstlane(__float_as_int(1.0f - lam_init)));
;                     const float* subg = ap->in[I_SUBG] + l * 128;
;                     if constexpr (PROBE_ATT2 != 0) { for (int i = 0; i < per; ++i) { const int u = vcu * per + i; if (u < 1024) attn_unit<false>(lds, (bf16_t*)(ws + WS_Q), (const bf16_t*)(ws + WS_K), (const bf16_t*)(ws + WS_VT), subg, lam, oscale, u, wave); } }
;                     for (int i = 0; i < per; ++i) { int u = vcu * per + i;
;                         if (G == 256) { const int bb = vcu >> 5, w = vcu & 31; u = ((bb * 8 + 2 * i + (w >> 4)) << 4) | (w & 15); }
;                         if (u < 1024) attn_unit<true>(lds, (bf16_t*)(ws + WS_Q), (const bf16_t*)(ws + WS_K), (const bf16_t*)(ws + WS_VT), subg, lam, oscale, u, wave); }
.Lph1_setup:
	v_mov_b32_e32 v0, v1
	s_load_dwordx8 s[40:47], s[0:1], 0x48
	v_mbcnt_lo_u32_b32 v0, -1, v0
	v_readlane_b32 s12, v254, 60
	v_mbcnt_hi_u32_b32 v0, -1, v0
	s_waitcnt lgkmcnt(0)
	s_mov_b32 s14, s12
	v_lshl_add_u32 v2, s14, 6, v0
	v_ashrrev_i32_e32 v3, 31, v2
	v_lshlrev_b64 v[2:3], 2, v[2:3]
	v_lshl_add_u64 v[4:5], s[40:41], 0, v[2:3]
	global_load_dword v0, v[4:5], off
	v_lshl_add_u64 v[4:5], s[42:43], 0, v[2:3]
	global_load_dword v6, v[4:5], off
	v_mov_b32_e32 v7, v195
	v_lshl_add_u64 v[4:5], s[44:45], 0, v[2:3]
	v_lshl_add_u64 v[2:3], s[46:47], 0, v[2:3]
	global_load_dword v4, v[4:5], off
	s_abs_i32 s7, s29
	global_load_dword v2, v[2:3], off
	v_cvt_f32_i32_e32 v5, s14
	v_cvt_f32_u32_e32 v8, s7
	s_mov_b32 s19, 0x3fb8aa3b
	s_add_i32 s12, s29, 0x3ff
	v_mul_f32_e32 v5, 0xbe99999a, v5
	v_rcp_iflag_f32_e32 v8, v8
	v_mul_f32_e32 v9, 0x3fb8aa3b, v5
	v_fma_f32 v10, v5, s19, -v9
	v_rndne_f32_e32 v11, v9
	v_fmac_f32_e32 v10, 0x32a5705f, v5
	v_sub_f32_e32 v9, v9, v11
	v_add_f32_e32 v9, v9, v10
	v_cvt_i32_f32_e32 v11, v11
	v_mul_f32_e32 v8, 0x4f7ffffe, v8
	v_exp_f32_e32 v9, v9
	v_cvt_u32_f32_e32 v8, v8
	s_mov_b32 s20, 0xc2ce8ed0
	v_readlane_b32 s13, v254, 61
	v_mov_b32_e32 v3, v195
	s_xor_b32 s14, s12, s29
	v_ldexp_f32 v9, v9, v11
	v_cmp_ngt_f32_e32 vcc, s20, v5
	s_mov_b32 s21, 0x42b17218
	s_abs_i32 s13, s12
	s_ashr_i32 s12, s14, 31
	v_lshlrev_b32_e32 v7, 2, v7
	v_readfirstlane_b32 s14, v8
	v_cndmask_b32_e32 v8, 0, v9, vcc
	v_cmp_nlt_f32_e32 vcc, s21, v5
	v_mov_b32_e32 v11, 0x7f800000
	v_lshlrev_b32_e32 v3, 2, v3
	v_xor_b32_e32 v10, 4, v7
	v_cndmask_b32_e32 v5, v11, v8, vcc
	v_xor_b32_e32 v16, 4, v3
	v_xor_b32_e32 v12, 8, v7
	v_xor_b32_e32 v17, 8, v3
	v_xor_b32_e32 v13, 16, v7
	v_xor_b32_e32 v18, 16, v3
	v_xor_b32_e32 v14, 32, v7
	v_xor_b32_e32 v19, 32, v3
	v_xor_b32_e32 v15, 64, v7
	v_xor_b32_e32 v20, 64, v3
	v_xor_b32_e32 v7, 0x80, v7
	v_xor_b32_e32 v3, 0x80, v3
	s_sub_i32 s15, 0, s7
	s_mul_i32 s15, s15, s14
	s_mul_hi_u32 s15, s14, s15
	s_add_i32 s14, s14, s15
	s_mul_hi_u32 s14, s13, s14
	s_mul_i32 s16, s14, s7
	s_sub_i32 s13, s13, s16
	s_add_i32 s18, s14, 1
	s_sub_i32 s16, s13, s7
	s_cmp_ge_u32 s13, s7
	s_cselect_b32 s14, s18, s14
	s_cselect_b32 s13, s16, s13
	s_add_i32 s16, s14, 1
	s_cmp_ge_u32 s13, s7
	s_cselect_b32 s7, s16, s14
	s_xor_b32 s7, s7, s12
	s_sub_i32 s7, s7, s12
	s_cmp_gt_i32 s7, 0
	s_cselect_b64 s[12:13], -1, 0
	v_writelane_b32 v254, s12, 62
	s_cmp_lt_i32 s7, 1
	s_waitcnt vmcnt(0)
	v_mul_f32_e32 v8, v0, v6
	ds_bpermute_b32 v8, v10, v8
	v_mov_b32_e32 v10, 0x3f4ccccd
	v_fmamk_f32 v5, v5, 0xbf19999a, v10
	v_writelane_b32 v254, s13, 63
	v_readfirstlane_b32 s15, v5
	s_waitcnt lgkmcnt(0)
	v_fmac_f32_e32 v8, v0, v6
	v_mul_f32_e32 v9, v4, v2
	ds_bpermute_b32 v9, v16, v9
	ds_bpermute_b32 v0, v12, v8
	v_readlane_b32 s12, v254, 59
	s_mul_i32 s39, s7, s12
	s_waitcnt lgkmcnt(1)
	v_fmac_f32_e32 v9, v4, v2
	ds_bpermute_b32 v2, v17, v9
	s_waitcnt lgkmcnt(1)
	v_add_f32_e32 v0, v8, v0
	ds_bpermute_b32 v4, v13, v0
	s_waitcnt lgkmcnt(1)
	v_add_f32_e32 v2, v9, v2
	ds_bpermute_b32 v6, v18, v2
	s_waitcnt lgkmcnt(1)
	v_add_f32_e32 v0, v0, v4
	ds_bpermute_b32 v4, v14, v0
	s_waitcnt lgkmcnt(1)
	v_add_f32_e32 v2, v2, v6
	ds_bpermute_b32 v6, v19, v2
	s_waitcnt lgkmcnt(1)
	v_add_f32_e32 v0, v0, v4
	ds_bpermute_b32 v4, v15, v0
	s_waitcnt lgkmcnt(1)
	v_add_f32_e32 v2, v2, v6
	ds_bpermute_b32 v6, v20, v2
	s_waitcnt lgkmcnt(1)
	v_add_f32_e32 v0, v0, v4
	ds_bpermute_b32 v4, v7, v0
	s_waitcnt lgkmcnt(1)
	v_add_f32_e32 v2, v2, v6
	ds_bpermute_b32 v3, v3, v2
	s_waitcnt lgkmcnt(1)
	v_add_f32_e32 v0, v0, v4
	v_cmp_ngt_f32_e32 vcc, s20, v0
	s_waitcnt lgkmcnt(0)
	v_add_f32_e32 v2, v2, v3
	v_mul_f32_e32 v3, 0x3fb8aa3b, v0
	v_mul_f32_e32 v4, 0x3fb8aa3b, v2
	v_fma_f32 v6, v0, s19, -v3
	v_rndne_f32_e32 v7, v3
	v_fma_f32 v8, v2, s19, -v4
	v_rndne_f32_e32 v9, v4
	v_fmac_f32_e32 v6, 0x32a5705f, v0
	v_sub_f32_e32 v3, v3, v7
	v_fmac_f32_e32 v8, 0x32a5705f, v2
	v_sub_f32_e32 v4, v4, v9
	v_add_f32_e32 v3, v3, v6
	v_cvt_i32_f32_e32 v7, v7
	v_add_f32_e32 v4, v4, v8
	v_exp_f32_e32 v3, v3
	v_cvt_i32_f32_e32 v9, v9
	v_exp_f32_e32 v4, v4
	v_ldexp_f32 v3, v3, v7
	v_cndmask_b32_e32 v3, 0, v3, vcc
	v_ldexp_f32 v4, v4, v9
	v_cmp_ngt_f32_e32 vcc, s20, v2
	s_nop 1
	v_cndmask_b32_e32 v4, 0, v4, vcc
	v_cmp_nlt_f32_e32 vcc, s21, v0
	s_nop 1
	v_cndmask_b32_e32 v0, v11, v3, vcc
	v_cmp_nlt_f32_e32 vcc, s21, v2
	s_nop 1
	v_cndmask_b32_e32 v2, v11, v4, vcc
	v_sub_f32_e32 v0, v0, v2
	v_add_f32_e32 v0, v5, v0
	s_nop 0
	v_readfirstlane_b32 s14, v0
	s_cbranch_scc1 .LBB0_672
	s_load_dwordx2 s[12:13], s[0:1], 0x68
	v_readlane_b32 s18, v254, 60
	v_readlane_b32 s19, v254, 61
	s_lshl_b32 s18, s18, 7
	s_ashr_i32 s19, s18, 31
	s_lshl_b64 s[18:19], s[18:19], 2
	s_waitcnt lgkmcnt(0)
	s_add_u32 s44, s12, s18
	s_addc_u32 s45, s13, s19
	s_cmpk_eq_i32 s29, 0x100
	v_readlane_b32 s13, v254, 59
	s_cselect_b64 s[46:47], -1, 0
	s_lshl_b32 s12, s13, 2
	s_and_b32 s12, s12, 0xffffff80
	s_and_b32 s13, s13, 31
	s_or_b32 s60, s12, s13
	s_add_u32 s48, s10, 0xed00000
	s_addc_u32 s49, s11, 0
	s_add_u32 s50, s10, 0x8d00000
	s_addc_u32 s51, s11, 0
	s_add_u32 s52, s10, 0xad00000
	v_sub_f32_e64 v192, 1.0, s15
	s_addc_u32 s53, s11, 0
	s_mov_b32 s15, s14
	s_mov_b32 s61, 0
	s_cmp_lg_u32 s101, 0
	s_cbranch_scc1 .Lph1_att
	s_bitcmp1_b32 s2, 0
	s_cbranch_scc0 .Lph1_att
	s_mov_b32 s101, 1
	v_readlane_b32 s12, v254, 60
	s_nop 0
	s_lshl_b32 s12, s12, 10
	s_ashr_i32 s13, s12, 31
	s_lshl_b64 s[12:13], s[12:13], 2
	v_writelane_b32 v255, s12, 0
	s_nop 0
	v_writelane_b32 v255, s13, 1
	s_branch .LBB0_847
.Lph1_att:
	s_branch .LBB0_576
.LBB0_574:
	s_barrier

; #define PH_ON(bit) if constexpr ((PHMASK & (bit)) != 0)
; __global__ void __launch_bounds__(NTHREADS, 2) fwd_megakernel(Args a_unused) {
;     ...
;                 PH_ON(2048) {
;                     const float* sw = ap->in[I_SGUW] + (size_t)l * 8 * 16384; const float* sb = ap->in[I_SGUB] + l * 1024; const float* lg = ap->in[I_SLNG] + l * DM; const float* lb2 = ap->in[I_SLNB] + l * DM;
;                     if constexpr (PROBE_SGU2 != 0) { for (int i = 0; i < per; ++i) { const int u = vcu * per + i; if (u < 1024) sgu_unit<false>(lds, (const bf16_t*)(ws + WS_GEL), (const float*)(ws + WS_STAT), (bf16_t*)(ws + WS_GU), sw, sb, lg, lb2, u, wave); } }
;                     for (int i = 0; i < per; ++i) { const int u = vcu * per + i; if (u < 1024) sgu_unit<true>(lds, (const bf16_t*)(ws + WS_GEL), (const float*)(ws + WS_STAT), (bf16_t*)(ws + WS_GU), sw, sb, lg, lb2, u, wave); }
.LBB0_847:
	s_cmp_eq_u32 s101, 2
	s_cbranch_scc1 .LBB0_854
	v_readlane_b32 s12, v254, 62
	v_readlane_b32 s13, v254, 63
	s_and_b64 vcc, exec, s[12:13]
	s_mov_b32 s53, 0x20000
	s_mov_b32 s52, 0x28000
	s_cbranch_vccz .LBB0_854
	s_load_dwordx8 s[40:47], s[0:1], 0x70
	v_readlane_b32 s12, v254, 60
	v_readlane_b32 s13, v254, 61
	s_mov_b32 s14, s12
	s_ashr_i32 s15, s12, 31
	v_readlane_b32 s12, v254, 59
	s_mul_i32 s34, s7, s12
	s_lshl_b64 s[12:13], s[14:15], 19
	s_waitcnt lgkmcnt(0)
	s_add_u32 s16, s44, s12
	s_addc_u32 s18, s45, s13
	v_readlane_b32 s14, v255, 0
	v_readlane_b32 s15, v255, 1
	s_add_u32 s12, s46, s14
	s_addc_u32 s13, s47, s15
	s_add_u32 s19, s40, s14
	s_addc_u32 s20, s41, s15
	s_add_u32 s21, s42, s14
	s_addc_u32 s28, s43, s15
	s_add_u32 s30, s10, 0xcd00000
	s_addc_u32 s36, s11, 0
	s_add_u32 s14, s10, 0x12d00000
	v_readlane_b32 s35, v253, 18
	s_addc_u32 s15, s11, 0
	s_lshl_b32 s35, s35, 1
	s_add_u32 s35, s10, s35
	s_addc_u32 s41, s11, 0
	s_add_u32 s40, s35, 0x10d00000
	s_addc_u32 s41, s41, 0
	s_lshl_b32 s42, s34, 4
	s_branch .LBB0_851

; #define PH_ON(bit) if constexpr ((PHMASK & (bit)) != 0)
; __global__ void __launch_bounds__(NTHREADS, 2) fwd_megakernel(Args a_unused) {
;     ...
;                 PH_ON(2048) {
;                     const float* sw = ap->in[I_SGUW] + (size_t)l * 8 * 16384; const float* sb = ap->in[I_SGUB] + l * 1024; const float* lg = ap->in[I_SLNG] + l * DM; const float* lb2 = ap->in[I_SLNB] + l * DM;
;                     if constexpr (PROBE_SGU2 != 0) { for (int i = 0; i < per; ++i) { const int u = vcu * per + i; if (u < 1024) sgu_unit<false>(lds, (const bf16_t*)(ws + WS_GEL), (const float*)(ws + WS_STAT), (bf16_t*)(ws + WS_GU), sw, sb, lg, lb2, u, wave); } }
;                     for (int i = 0; i < per; ++i) { const int u = vcu * per + i; if (u < 1024) sgu_unit<true>(lds, (const bf16_t*)(ws + WS_GEL), (const float*)(ws + WS_STAT), (bf16_t*)(ws + WS_GU), sw, sb, lg, lb2, u, wave); }
;                 } }
.LBB0_854:
	s_cmp_eq_u32 s101, 1
	s_cbranch_scc0 .Lph1_done
	s_mov_b32 s101, 2
	s_branch .Lph1_setup
.Lph1_done:
	s_mov_b32 s101, 0
	s_branch .LBB0_886
